# layer-0 input RMSNorm loop: four rows per iteration (16 loads in flight per wave instead of 8), on top of the combined micro-edit stack
# speedup vs baseline: 1.0054x; 1.0054x over previous
.LBB0_7:
.LBB0_8:
	s_waitcnt lgkmcnt(0)
	global_load_dwordx4 v[14:17], v[6:7], off offset:-3072
	global_load_dwordx4 v[18:21], v[6:7], off offset:-2048
	global_load_dwordx4 v[22:25], v[6:7], off offset:-1024
	global_load_dwordx4 v[26:29], v[6:7], off
	v_lshl_add_u64 v[50:51], v[6:7], 0, s[18:19]
	global_load_dwordx4 v[32:35], v[50:51], off offset:-3072
	global_load_dwordx4 v[36:39], v[50:51], off offset:-2048
	global_load_dwordx4 v[40:43], v[50:51], off offset:-1024
	global_load_dwordx4 v[44:47], v[50:51], off
	v_lshl_add_u64 v[100:101], v[50:51], 0, s[18:19]
	global_load_dwordx4 v[68:71], v[100:101], off offset:-3072
	global_load_dwordx4 v[72:75], v[100:101], off offset:-2048
	global_load_dwordx4 v[76:79], v[100:101], off offset:-1024
	global_load_dwordx4 v[80:83], v[100:101], off
	v_lshl_add_u64 v[106:107], v[100:101], 0, s[18:19]
	global_load_dwordx4 v[84:87], v[106:107], off offset:-3072
	global_load_dwordx4 v[88:91], v[106:107], off offset:-2048
	global_load_dwordx4 v[92:95], v[106:107], off offset:-1024
	global_load_dwordx4 v[96:99], v[106:107], off
	v_lshl_add_u64 v[52:53], v[4:5], 0, s[16:17]
	v_lshl_add_u64 v[54:55], v[2:3], 0, s[14:15]
	v_lshl_add_u64 v[102:103], v[52:53], 0, s[16:17]
	v_lshl_add_u64 v[104:105], v[54:55], 0, s[14:15]
	v_lshl_add_u64 v[108:109], v[102:103], 0, s[16:17]
	v_lshl_add_u64 v[110:111], v[104:105], 0, s[14:15]
	v_lshl_add_u64 v[56:57], s[10:11], 0, v[4:5]
	v_add_co_u32_e32 v56, vcc, s13, v56
	s_nop 1
	v_addc_co_u32_e32 v57, vcc, 0, v57, vcc
	v_lshl_add_u64 v[48:49], s[10:11], 0, v[52:53]
	v_add_co_u32_e32 v48, vcc, s13, v48
	s_nop 1
	v_addc_co_u32_e32 v49, vcc, 0, v49, vcc
	v_lshl_add_u64 v[112:113], s[10:11], 0, v[102:103]
	v_add_co_u32_e32 v112, vcc, s13, v112
	s_nop 1
	v_addc_co_u32_e32 v113, vcc, 0, v113, vcc
	v_lshl_add_u64 v[114:115], s[10:11], 0, v[108:109]
	v_add_co_u32_e32 v114, vcc, s13, v114
	s_nop 1
	v_addc_co_u32_e32 v115, vcc, 0, v115, vcc
	s_waitcnt vmcnt(15)
	v_cvt_pk_bf16_f32 v60, v14, v15
	v_cvt_pk_bf16_f32 v61, v16, v17
	global_store_dwordx2 v[56:57], v[60:61], off
	v_mul_f32_e32 v58, v15, v15
	v_mul_f32_e32 v59, v17, v17
	v_fmac_f32_e32 v58, v14, v14
	v_fmac_f32_e32 v59, v16, v16
	v_add_f32_e32 v30, v58, v59
	s_waitcnt vmcnt(15)
	v_cvt_pk_bf16_f32 v60, v18, v19
	v_cvt_pk_bf16_f32 v61, v20, v21
	global_store_dwordx2 v[56:57], v[60:61], off offset:512
	v_mul_f32_e32 v58, v19, v19
	v_mul_f32_e32 v59, v21, v21
	v_fmac_f32_e32 v58, v18, v18
	v_fmac_f32_e32 v59, v20, v20
	v_add_f32_e32 v58, v58, v59
	v_add_f32_e32 v30, v30, v58
	s_waitcnt vmcnt(15)
	v_cvt_pk_bf16_f32 v60, v22, v23
	v_cvt_pk_bf16_f32 v61, v24, v25
	global_store_dwordx2 v[56:57], v[60:61], off offset:1024
	v_mul_f32_e32 v58, v23, v23
	v_mul_f32_e32 v59, v25, v25
	v_fmac_f32_e32 v58, v22, v22
	v_fmac_f32_e32 v59, v24, v24
	v_add_f32_e32 v58, v58, v59
	v_add_f32_e32 v30, v30, v58
	s_waitcnt vmcnt(15)
	v_cvt_pk_bf16_f32 v60, v26, v27
	v_cvt_pk_bf16_f32 v61, v28, v29
	global_store_dwordx2 v[56:57], v[60:61], off offset:1536
	v_mul_f32_e32 v58, v27, v27
	v_mul_f32_e32 v59, v29, v29
	v_fmac_f32_e32 v58, v26, v26
	v_fmac_f32_e32 v59, v28, v28
	v_add_f32_e32 v58, v58, v59
	v_add_f32_e32 v30, v30, v58
	s_waitcnt vmcnt(15)
	v_cvt_pk_bf16_f32 v64, v32, v33
	v_cvt_pk_bf16_f32 v65, v34, v35
	global_store_dwordx2 v[48:49], v[64:65], off
	v_mul_f32_e32 v62, v33, v33
	v_mul_f32_e32 v63, v35, v35
	v_fmac_f32_e32 v62, v32, v32
	v_fmac_f32_e32 v63, v34, v34
	v_add_f32_e32 v31, v62, v63
	s_waitcnt vmcnt(15)
	v_cvt_pk_bf16_f32 v64, v36, v37
	v_cvt_pk_bf16_f32 v65, v38, v39
	global_store_dwordx2 v[48:49], v[64:65], off offset:512
	v_mul_f32_e32 v62, v37, v37
	v_mul_f32_e32 v63, v39, v39
	v_fmac_f32_e32 v62, v36, v36
	v_fmac_f32_e32 v63, v38, v38
	v_add_f32_e32 v62, v62, v63
	v_add_f32_e32 v31, v31, v62
	s_waitcnt vmcnt(15)
	v_cvt_pk_bf16_f32 v64, v40, v41
	v_cvt_pk_bf16_f32 v65, v42, v43
	global_store_dwordx2 v[48:49], v[64:65], off offset:1024
	v_mul_f32_e32 v62, v41, v41
	v_mul_f32_e32 v63, v43, v43
	v_fmac_f32_e32 v62, v40, v40
	v_fmac_f32_e32 v63, v42, v42
	v_add_f32_e32 v62, v62, v63
	v_add_f32_e32 v31, v31, v62
	s_waitcnt vmcnt(15)
	v_cvt_pk_bf16_f32 v64, v44, v45
	v_cvt_pk_bf16_f32 v65, v46, v47
	global_store_dwordx2 v[48:49], v[64:65], off offset:1536
	v_mul_f32_e32 v62, v45, v45
	v_mul_f32_e32 v63, v47, v47
	v_fmac_f32_e32 v62, v44, v44
	v_fmac_f32_e32 v63, v46, v46
	v_add_f32_e32 v62, v62, v63
	v_add_f32_e32 v31, v31, v62
	s_waitcnt vmcnt(15)
	v_cvt_pk_bf16_f32 v120, v68, v69
	v_cvt_pk_bf16_f32 v121, v70, v71
	global_store_dwordx2 v[112:113], v[120:121], off
	v_mul_f32_e32 v118, v69, v69
	v_mul_f32_e32 v119, v71, v71
	v_fmac_f32_e32 v118, v68, v68
	v_fmac_f32_e32 v119, v70, v70
	v_add_f32_e32 v116, v118, v119
	s_waitcnt vmcnt(15)
	v_cvt_pk_bf16_f32 v120, v72, v73
	v_cvt_pk_bf16_f32 v121, v74, v75
	global_store_dwordx2 v[112:113], v[120:121], off offset:512
	v_mul_f32_e32 v118, v73, v73
	v_mul_f32_e32 v119, v75, v75
	v_fmac_f32_e32 v118, v72, v72
	v_fmac_f32_e32 v119, v74, v74
	v_add_f32_e32 v118, v118, v119
	v_add_f32_e32 v116, v116, v118
	s_waitcnt vmcnt(15)
	v_cvt_pk_bf16_f32 v120, v76, v77
	v_cvt_pk_bf16_f32 v121, v78, v79
	global_store_dwordx2 v[112:113], v[120:121], off offset:1024
	v_mul_f32_e32 v118, v77, v77
	v_mul_f32_e32 v119, v79, v79
	v_fmac_f32_e32 v118, v76, v76
	v_fmac_f32_e32 v119, v78, v78
	v_add_f32_e32 v118, v118, v119
	v_add_f32_e32 v116, v116, v118
	s_waitcnt vmcnt(15)
	v_cvt_pk_bf16_f32 v120, v80, v81
	v_cvt_pk_bf16_f32 v121, v82, v83
	global_store_dwordx2 v[112:113], v[120:121], off offset:1536
	v_mul_f32_e32 v118, v81, v81
	v_mul_f32_e32 v119, v83, v83
	v_fmac_f32_e32 v118, v80, v80
	v_fmac_f32_e32 v119, v82, v82
	v_add_f32_e32 v118, v118, v119
	v_add_f32_e32 v116, v116, v118
	s_waitcnt vmcnt(15)
	v_cvt_pk_bf16_f32 v124, v84, v85
	v_cvt_pk_bf16_f32 v125, v86, v87
	global_store_dwordx2 v[114:115], v[124:125], off
	v_mul_f32_e32 v122, v85, v85
	v_mul_f32_e32 v123, v87, v87
	v_fmac_f32_e32 v122, v84, v84
	v_fmac_f32_e32 v123, v86, v86
	v_add_f32_e32 v117, v122, v123
	s_waitcnt vmcnt(15)
	v_cvt_pk_bf16_f32 v124, v88, v89
	v_cvt_pk_bf16_f32 v125, v90, v91
	global_store_dwordx2 v[114:115], v[124:125], off offset:512
	v_mul_f32_e32 v122, v89, v89
	v_mul_f32_e32 v123, v91, v91
	v_fmac_f32_e32 v122, v88, v88
	v_fmac_f32_e32 v123, v90, v90
	v_add_f32_e32 v122, v122, v123
	v_add_f32_e32 v117, v117, v122
	s_waitcnt vmcnt(15)
	v_cvt_pk_bf16_f32 v124, v92, v93
	v_cvt_pk_bf16_f32 v125, v94, v95
	global_store_dwordx2 v[114:115], v[124:125], off offset:1024
	v_mul_f32_e32 v122, v93, v93
	v_mul_f32_e32 v123, v95, v95
	v_fmac_f32_e32 v122, v92, v92
	v_fmac_f32_e32 v123, v94, v94
	v_add_f32_e32 v122, v122, v123
	v_add_f32_e32 v117, v117, v122
	s_waitcnt vmcnt(15)
	v_cvt_pk_bf16_f32 v124, v96, v97
	v_cvt_pk_bf16_f32 v125, v98, v99
	global_store_dwordx2 v[114:115], v[124:125], off offset:1536
	v_mul_f32_e32 v122, v97, v97
	v_mul_f32_e32 v123, v99, v99
	v_fmac_f32_e32 v122, v96, v96
	v_fmac_f32_e32 v123, v98, v98
	v_add_f32_e32 v122, v122, v123
	v_add_f32_e32 v117, v117, v122
	ds_bpermute_b32 v126, v8, v30
	ds_bpermute_b32 v127, v8, v31
	ds_bpermute_b32 v128, v8, v116
	ds_bpermute_b32 v129, v8, v117
	s_waitcnt lgkmcnt(3)
	v_add_f32_e32 v30, v30, v126
	s_waitcnt lgkmcnt(2)
	v_add_f32_e32 v31, v31, v127
	s_waitcnt lgkmcnt(1)
	v_add_f32_e32 v116, v116, v128
	s_waitcnt lgkmcnt(0)
	v_add_f32_e32 v117, v117, v129
	ds_bpermute_b32 v126, v9, v30
	ds_bpermute_b32 v127, v9, v31
	ds_bpermute_b32 v128, v9, v116
	ds_bpermute_b32 v129, v9, v117
	s_waitcnt lgkmcnt(3)
	v_add_f32_e32 v30, v30, v126
	s_waitcnt lgkmcnt(2)
	v_add_f32_e32 v31, v31, v127
	s_waitcnt lgkmcnt(1)
	v_add_f32_e32 v116, v116, v128
	s_waitcnt lgkmcnt(0)
	v_add_f32_e32 v117, v117, v129
	ds_bpermute_b32 v126, v10, v30
	ds_bpermute_b32 v127, v10, v31
	ds_bpermute_b32 v128, v10, v116
	ds_bpermute_b32 v129, v10, v117
	s_waitcnt lgkmcnt(3)
	v_add_f32_e32 v30, v30, v126
	s_waitcnt lgkmcnt(2)
	v_add_f32_e32 v31, v31, v127
	s_waitcnt lgkmcnt(1)
	v_add_f32_e32 v116, v116, v128
	s_waitcnt lgkmcnt(0)
	v_add_f32_e32 v117, v117, v129
	ds_bpermute_b32 v126, v11, v30
	ds_bpermute_b32 v127, v11, v31
	ds_bpermute_b32 v128, v11, v116
	ds_bpermute_b32 v129, v11, v117
	s_waitcnt lgkmcnt(3)
	v_add_f32_e32 v30, v30, v126
	s_waitcnt lgkmcnt(2)
	v_add_f32_e32 v31, v31, v127
	s_waitcnt lgkmcnt(1)
	v_add_f32_e32 v116, v116, v128
	s_waitcnt lgkmcnt(0)
	v_add_f32_e32 v117, v117, v129
	ds_bpermute_b32 v126, v12, v30
	ds_bpermute_b32 v127, v12, v31
	ds_bpermute_b32 v128, v12, v116
	ds_bpermute_b32 v129, v12, v117
	s_waitcnt lgkmcnt(3)
	v_add_f32_e32 v30, v30, v126
	s_waitcnt lgkmcnt(2)
	v_add_f32_e32 v31, v31, v127
	s_waitcnt lgkmcnt(1)
	v_add_f32_e32 v116, v116, v128
	s_waitcnt lgkmcnt(0)
	v_add_f32_e32 v117, v117, v129
	ds_bpermute_b32 v126, v13, v30
	ds_bpermute_b32 v127, v13, v31
	ds_bpermute_b32 v128, v13, v116
	ds_bpermute_b32 v129, v13, v117
	s_waitcnt lgkmcnt(3)
	v_add_f32_e32 v30, v30, v126
	s_waitcnt lgkmcnt(2)
	v_add_f32_e32 v31, v31, v127
	s_waitcnt lgkmcnt(1)
	v_add_f32_e32 v116, v116, v128
	s_waitcnt lgkmcnt(0)
	v_add_f32_e32 v117, v117, v129
	s_mov_b64 s[20:21], exec
	s_and_b64 exec, exec, s[2:3]
	v_cndmask_b32_e64 v138, 0, v30, s[4:5]
	v_cndmask_b32_e64 v139, 0, v31, s[4:5]
	v_cndmask_b32_e64 v140, 0, v116, s[4:5]
	v_cndmask_b32_e64 v141, 0, v117, s[4:5]
	v_lshl_add_u64 v[130:131], s[10:11], 0, v[2:3]
	v_lshl_add_u64 v[132:133], s[10:11], 0, v[54:55]
	v_lshl_add_u64 v[134:135], s[10:11], 0, v[104:105]
	v_lshl_add_u64 v[136:137], s[10:11], 0, v[110:111]
	global_store_dword v[130:131], v138, off
	global_store_dword v[132:133], v139, off
	global_store_dword v[134:135], v140, off
	global_store_dword v[136:137], v141, off
	s_mov_b64 exec, s[20:21]
	v_readlane_b32 s20, v248, 21
	s_lshl_b32 s20, s20, 2
	s_add_i32 s12, s12, s20
	v_lshl_add_u64 v[2:3], v[110:111], 0, s[14:15]
	v_lshl_add_u64 v[4:5], v[108:109], 0, s[16:17]
	v_lshl_add_u64 v[6:7], v[106:107], 0, s[18:19]
	s_cmpk_gt_i32 s12, 0x7fff
	v_readlane_b32 s20, v248, 21
	v_readlane_b32 s21, v248, 22
	s_cbranch_scc0 .LBB0_8
